# P0 adaLN partial GEMV loop restructured 2x4: 64 row loads per wave in flight (into free AGPRs) instead of 16
# speedup vs baseline: 1.0034x; 1.0034x over previous
.LBB0_55:
	s_mov_b64 s[70:71], 0x30000
	s_mov_b32 s5, 0xffe6e000
	v_add_co_u32_e64 v20, s[16:17], s5, v6
	s_mov_b32 s5, 0xfffee000
	v_add_co_u32_e64 v22, s[18:19], s5, v6
	s_mov_b32 s5, 0xffe74000
	v_add_co_u32_e64 v60, s[20:21], s5, v6
	s_mov_b32 s5, 0xffff4000
	v_add_co_u32_e64 v62, s[22:23], s5, v6
	s_mov_b32 s5, 0xffe7a000
	s_mov_b32 s0, 0xffe5c000
	s_mov_b32 s1, 0xffe62000
	s_mov_b32 s4, 0xffe68000
	v_add_co_u32_e64 v64, s[24:25], s5, v6
	s_movk_i32 s5, 0xa000
	v_add_co_u32_e32 v8, vcc, s0, v6
	s_mov_b32 s0, 0xfffdc000
	v_add_co_u32_e64 v12, s[8:9], s1, v6
	s_mov_b32 s1, 0xfffe2000
	v_add_co_u32_e64 v16, s[12:13], s4, v6
	s_mov_b32 s4, 0xfffe8000
	v_add_co_u32_e64 v66, s[26:27], s5, v6
	s_mov_b32 s5, 0xffe80000
	v_add_co_u32_e64 v10, s[6:7], s0, v6
	v_add_co_u32_e64 v14, s[10:11], s1, v6
	v_add_co_u32_e64 v18, s[14:15], s4, v6
	v_add_co_u32_e64 v68, s[28:29], s5, v6
	v_addc_co_u32_e32 v9, vcc, -1, v7, vcc
	v_addc_co_u32_e64 v11, vcc, -1, v7, s[6:7]
	v_addc_co_u32_e64 v13, vcc, -1, v7, s[8:9]
	v_addc_co_u32_e64 v15, vcc, -1, v7, s[10:11]
	v_addc_co_u32_e64 v17, vcc, -1, v7, s[12:13]
	v_addc_co_u32_e64 v19, vcc, -1, v7, s[14:15]
	v_addc_co_u32_e64 v21, vcc, -1, v7, s[16:17]
	v_addc_co_u32_e64 v23, vcc, -1, v7, s[18:19]
	v_addc_co_u32_e64 v61, vcc, -1, v7, s[20:21]
	v_addc_co_u32_e64 v63, vcc, -1, v7, s[22:23]
	v_addc_co_u32_e64 v65, vcc, -1, v7, s[24:25]
	v_addc_co_u32_e64 v67, vcc, -1, v7, s[26:27]
	v_addc_co_u32_e64 v69, vcc, -1, v7, s[28:29]
	v_add_co_u32_e32 v30, vcc, 0xffe56000, v6
	global_load_dword a6, v[6:7], off nt
	global_load_dword a7, v[22:23], off nt
	v_addc_co_u32_e32 v31, vcc, -1, v7, vcc
	v_add_co_u32_e32 v32, vcc, 0xfffd6000, v6
	s_nop 0
	v_addc_co_u32_e32 v33, vcc, -1, v7, vcc
	global_load_dword a8, v[20:21], off nt
	s_nop 0
	global_load_dword a9, v[60:61], off nt
	global_load_dword a10, v[62:63], off nt
	s_nop 0
	global_load_dword a11, v[64:65], off nt
	s_nop 0
	global_load_dword a12, v[66:67], off nt
	s_nop 0
	global_load_dword a13, v[10:11], off nt
	global_load_dword a14, v[14:15], off nt
	global_load_dword a15, v[18:19], off nt
	s_nop 0
	global_load_dword a16, v[8:9], off nt
	global_load_dword a17, v[12:13], off nt
	s_nop 0
	global_load_dword a18, v[16:17], off nt
	global_load_dword a19, v[30:31], off nt
	global_load_dword a20, v[32:33], off nt
	s_nop 0
	global_load_dword a21, v[68:69], off nt
	v_lshl_add_u64 v[6:7], v[6:7], 0, s[70:71]
	s_mov_b32 s5, 0xffe6e000
	v_add_co_u32_e64 v20, s[16:17], s5, v6
	s_mov_b32 s5, 0xfffee000
	v_add_co_u32_e64 v22, s[18:19], s5, v6
	s_mov_b32 s5, 0xffe74000
	v_add_co_u32_e64 v60, s[20:21], s5, v6
	s_mov_b32 s5, 0xffff4000
	v_add_co_u32_e64 v62, s[22:23], s5, v6
	s_mov_b32 s5, 0xffe7a000
	s_mov_b32 s0, 0xffe5c000
	s_mov_b32 s1, 0xffe62000
	s_mov_b32 s4, 0xffe68000
	v_add_co_u32_e64 v64, s[24:25], s5, v6
	s_movk_i32 s5, 0xa000
	v_add_co_u32_e32 v8, vcc, s0, v6
	s_mov_b32 s0, 0xfffdc000
	v_add_co_u32_e64 v12, s[8:9], s1, v6
	s_mov_b32 s1, 0xfffe2000
	v_add_co_u32_e64 v16, s[12:13], s4, v6
	s_mov_b32 s4, 0xfffe8000
	v_add_co_u32_e64 v66, s[26:27], s5, v6
	s_mov_b32 s5, 0xffe80000
	v_add_co_u32_e64 v10, s[6:7], s0, v6
	v_add_co_u32_e64 v14, s[10:11], s1, v6
	v_add_co_u32_e64 v18, s[14:15], s4, v6
	v_add_co_u32_e64 v68, s[28:29], s5, v6
	v_addc_co_u32_e32 v9, vcc, -1, v7, vcc
	v_addc_co_u32_e64 v11, vcc, -1, v7, s[6:7]
	v_addc_co_u32_e64 v13, vcc, -1, v7, s[8:9]
	v_addc_co_u32_e64 v15, vcc, -1, v7, s[10:11]
	v_addc_co_u32_e64 v17, vcc, -1, v7, s[12:13]
	v_addc_co_u32_e64 v19, vcc, -1, v7, s[14:15]
	v_addc_co_u32_e64 v21, vcc, -1, v7, s[16:17]
	v_addc_co_u32_e64 v23, vcc, -1, v7, s[18:19]
	v_addc_co_u32_e64 v61, vcc, -1, v7, s[20:21]
	v_addc_co_u32_e64 v63, vcc, -1, v7, s[22:23]
	v_addc_co_u32_e64 v65, vcc, -1, v7, s[24:25]
	v_addc_co_u32_e64 v67, vcc, -1, v7, s[26:27]
	v_addc_co_u32_e64 v69, vcc, -1, v7, s[28:29]
	v_add_co_u32_e32 v30, vcc, 0xffe56000, v6
	global_load_dword a22, v[6:7], off nt
	global_load_dword a23, v[22:23], off nt
	v_addc_co_u32_e32 v31, vcc, -1, v7, vcc
	v_add_co_u32_e32 v32, vcc, 0xfffd6000, v6
	s_nop 0
	v_addc_co_u32_e32 v33, vcc, -1, v7, vcc
	global_load_dword a24, v[20:21], off nt
	s_nop 0
	global_load_dword a25, v[60:61], off nt
	global_load_dword a26, v[62:63], off nt
	s_nop 0
	global_load_dword a27, v[64:65], off nt
	s_nop 0
	global_load_dword a28, v[66:67], off nt
	s_nop 0
	global_load_dword a29, v[10:11], off nt
	global_load_dword a30, v[14:15], off nt
	global_load_dword a31, v[18:19], off nt
	s_nop 0
	global_load_dword a32, v[8:9], off nt
	global_load_dword a33, v[12:13], off nt
	s_nop 0
	global_load_dword a34, v[16:17], off nt
	global_load_dword a35, v[30:31], off nt
	global_load_dword a36, v[32:33], off nt
	s_nop 0
	global_load_dword a37, v[68:69], off nt
	v_lshl_add_u64 v[6:7], v[6:7], 0, s[70:71]
	s_mov_b32 s5, 0xffe6e000
	v_add_co_u32_e64 v20, s[16:17], s5, v6
	s_mov_b32 s5, 0xfffee000
	v_add_co_u32_e64 v22, s[18:19], s5, v6
	s_mov_b32 s5, 0xffe74000
	v_add_co_u32_e64 v60, s[20:21], s5, v6
	s_mov_b32 s5, 0xffff4000
	v_add_co_u32_e64 v62, s[22:23], s5, v6
	s_mov_b32 s5, 0xffe7a000
	s_mov_b32 s0, 0xffe5c000
	s_mov_b32 s1, 0xffe62000
	s_mov_b32 s4, 0xffe68000
	v_add_co_u32_e64 v64, s[24:25], s5, v6
	s_movk_i32 s5, 0xa000
	v_add_co_u32_e32 v8, vcc, s0, v6
	s_mov_b32 s0, 0xfffdc000
	v_add_co_u32_e64 v12, s[8:9], s1, v6
	s_mov_b32 s1, 0xfffe2000
	v_add_co_u32_e64 v16, s[12:13], s4, v6
	s_mov_b32 s4, 0xfffe8000
	v_add_co_u32_e64 v66, s[26:27], s5, v6
	s_mov_b32 s5, 0xffe80000
	v_add_co_u32_e64 v10, s[6:7], s0, v6
	v_add_co_u32_e64 v14, s[10:11], s1, v6
	v_add_co_u32_e64 v18, s[14:15], s4, v6
	v_add_co_u32_e64 v68, s[28:29], s5, v6
	v_addc_co_u32_e32 v9, vcc, -1, v7, vcc
	v_addc_co_u32_e64 v11, vcc, -1, v7, s[6:7]
	v_addc_co_u32_e64 v13, vcc, -1, v7, s[8:9]
	v_addc_co_u32_e64 v15, vcc, -1, v7, s[10:11]
	v_addc_co_u32_e64 v17, vcc, -1, v7, s[12:13]
	v_addc_co_u32_e64 v19, vcc, -1, v7, s[14:15]
	v_addc_co_u32_e64 v21, vcc, -1, v7, s[16:17]
	v_addc_co_u32_e64 v23, vcc, -1, v7, s[18:19]
	v_addc_co_u32_e64 v61, vcc, -1, v7, s[20:21]
	v_addc_co_u32_e64 v63, vcc, -1, v7, s[22:23]
	v_addc_co_u32_e64 v65, vcc, -1, v7, s[24:25]
	v_addc_co_u32_e64 v67, vcc, -1, v7, s[26:27]
	v_addc_co_u32_e64 v69, vcc, -1, v7, s[28:29]
	v_add_co_u32_e32 v30, vcc, 0xffe56000, v6
	global_load_dword a38, v[6:7], off nt
	global_load_dword a39, v[22:23], off nt
	v_addc_co_u32_e32 v31, vcc, -1, v7, vcc
	v_add_co_u32_e32 v32, vcc, 0xfffd6000, v6
	s_nop 0
	v_addc_co_u32_e32 v33, vcc, -1, v7, vcc
	global_load_dword a40, v[20:21], off nt
	s_nop 0
	global_load_dword a41, v[60:61], off nt
	global_load_dword a42, v[62:63], off nt
	s_nop 0
	global_load_dword a43, v[64:65], off nt
	s_nop 0
	global_load_dword a44, v[66:67], off nt
	s_nop 0
	global_load_dword a45, v[10:11], off nt
	global_load_dword a46, v[14:15], off nt
	global_load_dword a47, v[18:19], off nt
	s_nop 0
	global_load_dword a48, v[8:9], off nt
	global_load_dword a49, v[12:13], off nt
	s_nop 0
	global_load_dword a50, v[16:17], off nt
	global_load_dword a51, v[30:31], off nt
	global_load_dword a52, v[32:33], off nt
	s_nop 0
	global_load_dword a53, v[68:69], off nt
	v_lshl_add_u64 v[6:7], v[6:7], 0, s[70:71]
	s_mov_b32 s5, 0xffe6e000
	v_add_co_u32_e64 v20, s[16:17], s5, v6
	s_mov_b32 s5, 0xfffee000
	v_add_co_u32_e64 v22, s[18:19], s5, v6
	s_mov_b32 s5, 0xffe74000
	v_add_co_u32_e64 v60, s[20:21], s5, v6
	s_mov_b32 s5, 0xffff4000
	v_add_co_u32_e64 v62, s[22:23], s5, v6
	s_mov_b32 s5, 0xffe7a000
	s_mov_b32 s0, 0xffe5c000
	s_mov_b32 s1, 0xffe62000
	s_mov_b32 s4, 0xffe68000
	v_add_co_u32_e64 v64, s[24:25], s5, v6
	s_movk_i32 s5, 0xa000
	v_add_co_u32_e32 v8, vcc, s0, v6
	s_mov_b32 s0, 0xfffdc000
	v_add_co_u32_e64 v12, s[8:9], s1, v6
	s_mov_b32 s1, 0xfffe2000
	v_add_co_u32_e64 v16, s[12:13], s4, v6
	s_mov_b32 s4, 0xfffe8000
	v_add_co_u32_e64 v66, s[26:27], s5, v6
	s_mov_b32 s5, 0xffe80000
	v_add_co_u32_e64 v10, s[6:7], s0, v6
	v_add_co_u32_e64 v14, s[10:11], s1, v6
	v_add_co_u32_e64 v18, s[14:15], s4, v6
	v_add_co_u32_e64 v68, s[28:29], s5, v6
	v_addc_co_u32_e32 v9, vcc, -1, v7, vcc
	v_addc_co_u32_e64 v11, vcc, -1, v7, s[6:7]
	v_addc_co_u32_e64 v13, vcc, -1, v7, s[8:9]
	v_addc_co_u32_e64 v15, vcc, -1, v7, s[10:11]
	v_addc_co_u32_e64 v17, vcc, -1, v7, s[12:13]
	v_addc_co_u32_e64 v19, vcc, -1, v7, s[14:15]
	v_addc_co_u32_e64 v21, vcc, -1, v7, s[16:17]
	v_addc_co_u32_e64 v23, vcc, -1, v7, s[18:19]
	v_addc_co_u32_e64 v61, vcc, -1, v7, s[20:21]
	v_addc_co_u32_e64 v63, vcc, -1, v7, s[22:23]
	v_addc_co_u32_e64 v65, vcc, -1, v7, s[24:25]
	v_addc_co_u32_e64 v67, vcc, -1, v7, s[26:27]
	v_addc_co_u32_e64 v69, vcc, -1, v7, s[28:29]
	v_add_co_u32_e32 v30, vcc, 0xffe56000, v6
	global_load_dword a54, v[6:7], off nt
	global_load_dword a55, v[22:23], off nt
	v_addc_co_u32_e32 v31, vcc, -1, v7, vcc
	v_add_co_u32_e32 v32, vcc, 0xfffd6000, v6
	s_nop 0
	v_addc_co_u32_e32 v33, vcc, -1, v7, vcc
	global_load_dword a56, v[20:21], off nt
	s_nop 0
	global_load_dword a57, v[60:61], off nt
	global_load_dword a58, v[62:63], off nt
	s_nop 0
	global_load_dword a59, v[64:65], off nt
	s_nop 0
	global_load_dword a60, v[66:67], off nt
	s_nop 0
	global_load_dword a61, v[10:11], off nt
	global_load_dword a62, v[14:15], off nt
	global_load_dword a63, v[18:19], off nt
	s_nop 0
	global_load_dword a64, v[8:9], off nt
	global_load_dword a65, v[12:13], off nt
	s_nop 0
	global_load_dword a66, v[16:17], off nt
	global_load_dword a67, v[30:31], off nt
	global_load_dword a68, v[32:33], off nt
	s_nop 0
	global_load_dword a69, v[68:69], off nt
	v_lshl_add_u64 v[6:7], v[6:7], 0, s[70:71]
	s_add_i32 s0, s33, 1
	s_add_i32 s1, s33, 2
	s_add_i32 s4, s33, 3
	s_add_i32 s34, s33, 4
	s_add_i32 s35, s33, 5
	s_add_i32 s57, s33, 7
	s_add_i32 s43, s33, 6
	v_readlane_b32 s10, v45, s0
	v_readlane_b32 s24, v47, s0
	v_readlane_b32 s11, v51, s0
	v_readlane_b32 s25, v49, s0
	v_readlane_b32 s12, v53, s0
	v_readlane_b32 s26, v55, s0
	v_readlane_b32 s13, v57, s0
	v_readlane_b32 s27, v59, s0
	v_readlane_b32 s6, v71, s0
	v_readlane_b32 s7, v88, s0
	v_readlane_b32 s16, v45, s1
	v_readlane_b32 s94, v47, s1
	v_readlane_b32 s17, v51, s1
	v_readlane_b32 s95, v49, s1
	v_readlane_b32 s18, v53, s1
	v_readlane_b32 s96, v55, s1
	v_readlane_b32 s19, v57, s1
	v_readlane_b32 s97, v59, s1
	v_readlane_b32 s8, v71, s1
	v_readlane_b32 s9, v88, s1
	v_readlane_b32 s20, v45, s4
	v_readlane_b32 s38, v47, s4
	v_readlane_b32 s21, v51, s4
	v_readlane_b32 s39, v49, s4
	v_readlane_b32 s22, v53, s4
	v_readlane_b32 s40, v55, s4
	v_readlane_b32 s23, v57, s4
	v_readlane_b32 s41, v59, s4
	v_readlane_b32 s14, v71, s4
	v_readlane_b32 s15, v88, s4
	v_readlane_b32 s44, v45, s34
	v_readlane_b32 s4, v47, s34
	v_readlane_b32 s45, v51, s34
	v_readlane_b32 s5, v49, s34
	v_readlane_b32 s46, v53, s34
	v_readlane_b32 s68, v55, s34
	v_readlane_b32 s47, v57, s34
	v_readlane_b32 s69, v59, s34
	v_readlane_b32 s28, v71, s34
	v_readlane_b32 s29, v88, s34
	v_readlane_b32 s48, v45, s35
	v_readlane_b32 s58, v47, s35
	v_readlane_b32 s49, v51, s35
	v_readlane_b32 s59, v49, s35
	v_readlane_b32 s50, v53, s35
	v_readlane_b32 s60, v55, s35
	v_readlane_b32 s51, v57, s35
	v_readlane_b32 s61, v59, s35
	v_readlane_b32 s36, v71, s35
	v_readlane_b32 s37, v88, s35
	v_readlane_b32 s0, v47, s57
	v_readlane_b32 s1, v49, s57
	v_readlane_b32 s34, v55, s57
	v_readlane_b32 s35, v59, s57
	v_readlane_b32 s64, v47, s43
	v_readlane_b32 s65, v49, s43
	v_readlane_b32 s92, v55, s43
	v_readlane_b32 s93, v59, s43
	v_readlane_b32 s62, v45, s57
	v_readlane_b32 s63, v51, s57
	v_readlane_b32 s66, v53, s57
	v_readlane_b32 s67, v57, s57
	v_readlane_b32 s52, v45, s43
	v_readlane_b32 s53, v51, s43
	s_waitcnt vmcnt(48)
	v_accvgpr_read_b32 v24, a6
	v_accvgpr_read_b32 v70, a7
	v_accvgpr_read_b32 v22, a8
	v_accvgpr_read_b32 v20, a9
	v_accvgpr_read_b32 v76, a10
	v_accvgpr_read_b32 v60, a11
	v_accvgpr_read_b32 v66, a12
	v_accvgpr_read_b32 v64, a13
	v_accvgpr_read_b32 v62, a14
	v_accvgpr_read_b32 v26, a15
	v_accvgpr_read_b32 v18, a16
	v_accvgpr_read_b32 v14, a17
	v_accvgpr_read_b32 v12, a18
	v_accvgpr_read_b32 v8, a19
	v_accvgpr_read_b32 v10, a20
	v_accvgpr_read_b32 v16, a21
	v_pk_mul_f32 v[72:73], v[24:25], s[0:1] op_sel_hi:[0,1]
	v_pk_mul_f32 v[78:79], v[24:25], s[34:35] op_sel_hi:[0,1]
	v_readlane_b32 s54, v53, s43
	v_readlane_b32 s55, v57, s43
	v_readlane_b32 s56, v71, s57
	v_readlane_b32 s57, v88, s57
	v_readlane_b32 s0, v47, s33
	v_readlane_b32 s1, v49, s33
	v_pk_mul_f32 v[74:75], v[70:71], s[4:5] op_sel_hi:[0,1]
	v_readlane_b32 s4, v55, s33
	v_readlane_b32 s5, v59, s33
	v_pk_mul_f32 v[80:81], v[66:67], s[64:65] op_sel_hi:[0,1]
	v_pk_mul_f32 v[102:103], v[66:67], s[92:93] op_sel_hi:[0,1]
	v_pk_fma_f32 v[72:73], v[16:17], s[62:63], v[72:73] op_sel_hi:[0,1,1]
	v_pk_fma_f32 v[78:79], v[16:17], s[66:67], v[78:79] op_sel_hi:[0,1,1]
	v_mov_b32_e32 v17, v24
	v_pk_mul_f32 v[104:105], v[64:65], s[24:25] op_sel_hi:[0,1]
	v_pk_mul_f32 v[112:113], v[64:65], s[26:27] op_sel_hi:[0,1]
	v_pk_mul_f32 v[114:115], v[62:63], s[94:95] op_sel_hi:[0,1]
	v_pk_mul_f32 v[116:117], v[62:63], s[96:97] op_sel_hi:[0,1]
	v_pk_mul_f32 v[118:119], v[26:27], s[38:39] op_sel_hi:[0,1]
	v_readlane_b32 vcc_lo, v45, s33
	v_readlane_b32 vcc_hi, v51, s33
	v_readlane_b32 s34, v53, s33
	v_readlane_b32 s35, v57, s33
	v_pk_fma_f32 v[80:81], v[60:61], s[52:53], v[80:81] op_sel_hi:[0,1,1]
	v_pk_fma_f32 v[102:103], v[60:61], s[54:55], v[102:103] op_sel_hi:[0,1,1]
	v_mov_b32_e32 v61, v66
	v_pk_mul_f32 v[16:17], v[16:17], s[56:57]
	v_pk_fma_f32 v[66:67], v[18:19], s[10:11], v[104:105] op_sel_hi:[0,1,1]
	v_pk_fma_f32 v[104:105], v[18:19], s[12:13], v[112:113] op_sel_hi:[0,1,1]
	v_mov_b32_e32 v19, v64
	v_pk_fma_f32 v[64:65], v[14:15], s[16:17], v[114:115] op_sel_hi:[0,1,1]
	v_pk_fma_f32 v[112:113], v[14:15], s[18:19], v[116:117] op_sel_hi:[0,1,1]
	v_mov_b32_e32 v15, v62
	v_pk_fma_f32 v[62:63], v[12:13], s[20:21], v[118:119] op_sel_hi:[0,1,1]
	v_pk_mul_f32 v[116:117], v[10:11], s[0:1] op_sel_hi:[0,1]
	v_pk_mul_f32 v[118:119], v[10:11], s[4:5] op_sel_hi:[0,1]
	v_pk_mul_f32 v[68:69], v[70:71], s[68:69] op_sel_hi:[0,1]
	v_readlane_b32 s68, v71, s33
	v_readlane_b32 s69, v88, s33
	v_add_f32_e32 v11, v16, v17
	v_pk_mul_f32 v[16:17], v[18:19], s[6:7]
	v_pk_fma_f32 v[18:19], v[8:9], vcc, v[116:117] op_sel_hi:[0,1,1]
	v_pk_fma_f32 v[116:117], v[8:9], s[34:35], v[118:119] op_sel_hi:[0,1,1]
	v_mov_b32_e32 v9, v10
	v_pk_mul_f32 v[8:9], v[8:9], s[68:69]
	v_pk_mul_f32 v[120:121], v[26:27], s[40:41] op_sel_hi:[0,1]
	v_add_f32_e32 v8, v8, v9
	v_pk_fma_f32 v[114:115], v[12:13], s[22:23], v[120:121] op_sel_hi:[0,1,1]
	v_mov_b32_e32 v13, v26
	v_pk_mul_f32 v[14:15], v[14:15], s[8:9]
	v_add_f32_e32 v16, v16, v17
	v_pk_add_f32 v[2:3], v[2:3], v[18:19]
	v_pk_add_f32 v[0:1], v[0:1], v[116:117]
	v_add_f32_e32 v8, v43, v8
	v_pk_mul_f32 v[30:31], v[76:77], s[58:59] op_sel_hi:[0,1]
	v_pk_mul_f32 v[32:33], v[76:77], s[60:61] op_sel_hi:[0,1]
	v_pk_fma_f32 v[74:75], v[22:23], s[44:45], v[74:75] op_sel_hi:[0,1,1]
	v_pk_fma_f32 v[68:69], v[22:23], s[46:47], v[68:69] op_sel_hi:[0,1,1]
	v_mov_b32_e32 v23, v70
	v_pk_mul_f32 v[12:13], v[12:13], s[14:15]
	v_add_f32_e32 v14, v14, v15
	v_pk_add_f32 v[2:3], v[2:3], v[66:67]
	v_pk_add_f32 v[0:1], v[0:1], v[104:105]
	v_add_f32_e32 v8, v8, v16
	v_pk_fma_f32 v[30:31], v[20:21], s[48:49], v[30:31] op_sel_hi:[0,1,1]
	v_pk_fma_f32 v[32:33], v[20:21], s[50:51], v[32:33] op_sel_hi:[0,1,1]
	v_mov_b32_e32 v21, v76
	v_pk_mul_f32 v[22:23], v[22:23], s[28:29]
	v_add_f32_e32 v12, v12, v13
	v_pk_add_f32 v[2:3], v[2:3], v[64:65]
	v_pk_add_f32 v[0:1], v[0:1], v[112:113]
	v_add_f32_e32 v8, v8, v14
	v_readlane_b32 s42, v71, s43
	v_readlane_b32 s43, v88, s43
	v_pk_mul_f32 v[20:21], v[20:21], s[36:37]
	v_add_f32_e32 v10, v22, v23
	v_pk_add_f32 v[2:3], v[2:3], v[62:63]
	v_pk_add_f32 v[0:1], v[0:1], v[114:115]
	v_add_f32_e32 v8, v8, v12
	v_pk_mul_f32 v[60:61], v[60:61], s[42:43]
	v_add_f32_e32 v20, v20, v21
	v_pk_add_f32 v[2:3], v[2:3], v[74:75]
	v_pk_add_f32 v[0:1], v[0:1], v[68:69]
	v_add_f32_e32 v8, v8, v10
	v_add_f32_e32 v21, v60, v61
	v_pk_add_f32 v[2:3], v[2:3], v[30:31]
	v_pk_add_f32 v[0:1], v[0:1], v[32:33]
	v_add_f32_e32 v8, v8, v20
	s_add_i32 s33, s33, 8
	v_pk_add_f32 v[2:3], v[2:3], v[80:81]
	v_pk_add_f32 v[0:1], v[0:1], v[102:103]
	v_add_f32_e32 v8, v8, v21
	v_pk_add_f32 v[2:3], v[2:3], v[72:73]
	v_pk_add_f32 v[0:1], v[0:1], v[78:79]
	v_add_f32_e32 v43, v8, v11
	s_add_i32 s0, s33, 1
	s_add_i32 s1, s33, 2
	s_add_i32 s4, s33, 3
	s_add_i32 s34, s33, 4
	s_add_i32 s35, s33, 5
	s_add_i32 s57, s33, 7
	s_add_i32 s43, s33, 6
	v_readlane_b32 s10, v45, s0
	v_readlane_b32 s24, v47, s0
	v_readlane_b32 s11, v51, s0
	v_readlane_b32 s25, v49, s0
	v_readlane_b32 s12, v53, s0
	v_readlane_b32 s26, v55, s0
	v_readlane_b32 s13, v57, s0
	v_readlane_b32 s27, v59, s0
	v_readlane_b32 s6, v71, s0
	v_readlane_b32 s7, v88, s0
	v_readlane_b32 s16, v45, s1
	v_readlane_b32 s94, v47, s1
	v_readlane_b32 s17, v51, s1
	v_readlane_b32 s95, v49, s1
	v_readlane_b32 s18, v53, s1
	v_readlane_b32 s96, v55, s1
	v_readlane_b32 s19, v57, s1
	v_readlane_b32 s97, v59, s1
	v_readlane_b32 s8, v71, s1
	v_readlane_b32 s9, v88, s1
	v_readlane_b32 s20, v45, s4
	v_readlane_b32 s38, v47, s4
	v_readlane_b32 s21, v51, s4
	v_readlane_b32 s39, v49, s4
	v_readlane_b32 s22, v53, s4
	v_readlane_b32 s40, v55, s4
	v_readlane_b32 s23, v57, s4
	v_readlane_b32 s41, v59, s4
	v_readlane_b32 s14, v71, s4
	v_readlane_b32 s15, v88, s4
	v_readlane_b32 s44, v45, s34
	v_readlane_b32 s4, v47, s34
	v_readlane_b32 s45, v51, s34
	v_readlane_b32 s5, v49, s34
	v_readlane_b32 s46, v53, s34
	v_readlane_b32 s68, v55, s34
	v_readlane_b32 s47, v57, s34
	v_readlane_b32 s69, v59, s34
	v_readlane_b32 s28, v71, s34
	v_readlane_b32 s29, v88, s34
	v_readlane_b32 s48, v45, s35
	v_readlane_b32 s58, v47, s35
	v_readlane_b32 s49, v51, s35
	v_readlane_b32 s59, v49, s35
	v_readlane_b32 s50, v53, s35
	v_readlane_b32 s60, v55, s35
	v_readlane_b32 s51, v57, s35
	v_readlane_b32 s61, v59, s35
	v_readlane_b32 s36, v71, s35
	v_readlane_b32 s37, v88, s35
	v_readlane_b32 s0, v47, s57
	v_readlane_b32 s1, v49, s57
	v_readlane_b32 s34, v55, s57
	v_readlane_b32 s35, v59, s57
	v_readlane_b32 s64, v47, s43
	v_readlane_b32 s65, v49, s43
	v_readlane_b32 s92, v55, s43
	v_readlane_b32 s93, v59, s43
	v_readlane_b32 s62, v45, s57
	v_readlane_b32 s63, v51, s57
	v_readlane_b32 s66, v53, s57
	v_readlane_b32 s67, v57, s57
	v_readlane_b32 s52, v45, s43
	v_readlane_b32 s53, v51, s43
	s_waitcnt vmcnt(32)
	v_accvgpr_read_b32 v24, a22
	v_accvgpr_read_b32 v70, a23
	v_accvgpr_read_b32 v22, a24
	v_accvgpr_read_b32 v20, a25
	v_accvgpr_read_b32 v76, a26
	v_accvgpr_read_b32 v60, a27
	v_accvgpr_read_b32 v66, a28
	v_accvgpr_read_b32 v64, a29
	v_accvgpr_read_b32 v62, a30
	v_accvgpr_read_b32 v26, a31
	v_accvgpr_read_b32 v18, a32
	v_accvgpr_read_b32 v14, a33
	v_accvgpr_read_b32 v12, a34
	v_accvgpr_read_b32 v8, a35
	v_accvgpr_read_b32 v10, a36
	v_accvgpr_read_b32 v16, a37
	v_pk_mul_f32 v[72:73], v[24:25], s[0:1] op_sel_hi:[0,1]
	v_pk_mul_f32 v[78:79], v[24:25], s[34:35] op_sel_hi:[0,1]
	v_readlane_b32 s54, v53, s43
	v_readlane_b32 s55, v57, s43
	v_readlane_b32 s56, v71, s57
	v_readlane_b32 s57, v88, s57
	v_readlane_b32 s0, v47, s33
	v_readlane_b32 s1, v49, s33
	v_pk_mul_f32 v[74:75], v[70:71], s[4:5] op_sel_hi:[0,1]
	v_readlane_b32 s4, v55, s33
	v_readlane_b32 s5, v59, s33
	v_pk_mul_f32 v[80:81], v[66:67], s[64:65] op_sel_hi:[0,1]
	v_pk_mul_f32 v[102:103], v[66:67], s[92:93] op_sel_hi:[0,1]
	v_pk_fma_f32 v[72:73], v[16:17], s[62:63], v[72:73] op_sel_hi:[0,1,1]
	v_pk_fma_f32 v[78:79], v[16:17], s[66:67], v[78:79] op_sel_hi:[0,1,1]
	v_mov_b32_e32 v17, v24
	v_pk_mul_f32 v[104:105], v[64:65], s[24:25] op_sel_hi:[0,1]
	v_pk_mul_f32 v[112:113], v[64:65], s[26:27] op_sel_hi:[0,1]
	v_pk_mul_f32 v[114:115], v[62:63], s[94:95] op_sel_hi:[0,1]
	v_pk_mul_f32 v[116:117], v[62:63], s[96:97] op_sel_hi:[0,1]
	v_pk_mul_f32 v[118:119], v[26:27], s[38:39] op_sel_hi:[0,1]
	v_readlane_b32 vcc_lo, v45, s33
	v_readlane_b32 vcc_hi, v51, s33
	v_readlane_b32 s34, v53, s33
	v_readlane_b32 s35, v57, s33
	v_pk_fma_f32 v[80:81], v[60:61], s[52:53], v[80:81] op_sel_hi:[0,1,1]
	v_pk_fma_f32 v[102:103], v[60:61], s[54:55], v[102:103] op_sel_hi:[0,1,1]
	v_mov_b32_e32 v61, v66
	v_pk_mul_f32 v[16:17], v[16:17], s[56:57]
	v_pk_fma_f32 v[66:67], v[18:19], s[10:11], v[104:105] op_sel_hi:[0,1,1]
	v_pk_fma_f32 v[104:105], v[18:19], s[12:13], v[112:113] op_sel_hi:[0,1,1]
	v_mov_b32_e32 v19, v64
	v_pk_fma_f32 v[64:65], v[14:15], s[16:17], v[114:115] op_sel_hi:[0,1,1]
	v_pk_fma_f32 v[112:113], v[14:15], s[18:19], v[116:117] op_sel_hi:[0,1,1]
	v_mov_b32_e32 v15, v62
	v_pk_fma_f32 v[62:63], v[12:13], s[20:21], v[118:119] op_sel_hi:[0,1,1]
	v_pk_mul_f32 v[116:117], v[10:11], s[0:1] op_sel_hi:[0,1]
	v_pk_mul_f32 v[118:119], v[10:11], s[4:5] op_sel_hi:[0,1]
	v_pk_mul_f32 v[68:69], v[70:71], s[68:69] op_sel_hi:[0,1]
	v_readlane_b32 s68, v71, s33
	v_readlane_b32 s69, v88, s33
	v_add_f32_e32 v11, v16, v17
	v_pk_mul_f32 v[16:17], v[18:19], s[6:7]
	v_pk_fma_f32 v[18:19], v[8:9], vcc, v[116:117] op_sel_hi:[0,1,1]
	v_pk_fma_f32 v[116:117], v[8:9], s[34:35], v[118:119] op_sel_hi:[0,1,1]
	v_mov_b32_e32 v9, v10
	v_pk_mul_f32 v[8:9], v[8:9], s[68:69]
	v_pk_mul_f32 v[120:121], v[26:27], s[40:41] op_sel_hi:[0,1]
	v_add_f32_e32 v8, v8, v9
	v_pk_fma_f32 v[114:115], v[12:13], s[22:23], v[120:121] op_sel_hi:[0,1,1]
	v_mov_b32_e32 v13, v26
	v_pk_mul_f32 v[14:15], v[14:15], s[8:9]
	v_add_f32_e32 v16, v16, v17
	v_pk_add_f32 v[2:3], v[2:3], v[18:19]
	v_pk_add_f32 v[0:1], v[0:1], v[116:117]
	v_add_f32_e32 v8, v43, v8
	v_pk_mul_f32 v[30:31], v[76:77], s[58:59] op_sel_hi:[0,1]
	v_pk_mul_f32 v[32:33], v[76:77], s[60:61] op_sel_hi:[0,1]
	v_pk_fma_f32 v[74:75], v[22:23], s[44:45], v[74:75] op_sel_hi:[0,1,1]
	v_pk_fma_f32 v[68:69], v[22:23], s[46:47], v[68:69] op_sel_hi:[0,1,1]
	v_mov_b32_e32 v23, v70
	v_pk_mul_f32 v[12:13], v[12:13], s[14:15]
	v_add_f32_e32 v14, v14, v15
	v_pk_add_f32 v[2:3], v[2:3], v[66:67]
	v_pk_add_f32 v[0:1], v[0:1], v[104:105]
	v_add_f32_e32 v8, v8, v16
	v_pk_fma_f32 v[30:31], v[20:21], s[48:49], v[30:31] op_sel_hi:[0,1,1]
	v_pk_fma_f32 v[32:33], v[20:21], s[50:51], v[32:33] op_sel_hi:[0,1,1]
	v_mov_b32_e32 v21, v76
	v_pk_mul_f32 v[22:23], v[22:23], s[28:29]
	v_add_f32_e32 v12, v12, v13
	v_pk_add_f32 v[2:3], v[2:3], v[64:65]
	v_pk_add_f32 v[0:1], v[0:1], v[112:113]
	v_add_f32_e32 v8, v8, v14
	v_readlane_b32 s42, v71, s43
	v_readlane_b32 s43, v88, s43
	v_pk_mul_f32 v[20:21], v[20:21], s[36:37]
	v_add_f32_e32 v10, v22, v23
	v_pk_add_f32 v[2:3], v[2:3], v[62:63]
	v_pk_add_f32 v[0:1], v[0:1], v[114:115]
	v_add_f32_e32 v8, v8, v12
	v_pk_mul_f32 v[60:61], v[60:61], s[42:43]
	v_add_f32_e32 v20, v20, v21
	v_pk_add_f32 v[2:3], v[2:3], v[74:75]
	v_pk_add_f32 v[0:1], v[0:1], v[68:69]
	v_add_f32_e32 v8, v8, v10
	v_add_f32_e32 v21, v60, v61
	v_pk_add_f32 v[2:3], v[2:3], v[30:31]
	v_pk_add_f32 v[0:1], v[0:1], v[32:33]
	v_add_f32_e32 v8, v8, v20
	s_add_i32 s33, s33, 8
	v_pk_add_f32 v[2:3], v[2:3], v[80:81]
	v_pk_add_f32 v[0:1], v[0:1], v[102:103]
	v_add_f32_e32 v8, v8, v21
	v_pk_add_f32 v[2:3], v[2:3], v[72:73]
	v_pk_add_f32 v[0:1], v[0:1], v[78:79]
	v_add_f32_e32 v43, v8, v11
	s_add_i32 s0, s33, 1
	s_add_i32 s1, s33, 2
	s_add_i32 s4, s33, 3
	s_add_i32 s34, s33, 4
	s_add_i32 s35, s33, 5
	s_add_i32 s57, s33, 7
	s_add_i32 s43, s33, 6
	v_readlane_b32 s10, v45, s0
	v_readlane_b32 s24, v47, s0
	v_readlane_b32 s11, v51, s0
	v_readlane_b32 s25, v49, s0
	v_readlane_b32 s12, v53, s0
	v_readlane_b32 s26, v55, s0
	v_readlane_b32 s13, v57, s0
	v_readlane_b32 s27, v59, s0
	v_readlane_b32 s6, v71, s0
	v_readlane_b32 s7, v88, s0
	v_readlane_b32 s16, v45, s1
	v_readlane_b32 s94, v47, s1
	v_readlane_b32 s17, v51, s1
	v_readlane_b32 s95, v49, s1
	v_readlane_b32 s18, v53, s1
	v_readlane_b32 s96, v55, s1
	v_readlane_b32 s19, v57, s1
	v_readlane_b32 s97, v59, s1
	v_readlane_b32 s8, v71, s1
	v_readlane_b32 s9, v88, s1
	v_readlane_b32 s20, v45, s4
	v_readlane_b32 s38, v47, s4
	v_readlane_b32 s21, v51, s4
	v_readlane_b32 s39, v49, s4
	v_readlane_b32 s22, v53, s4
	v_readlane_b32 s40, v55, s4
	v_readlane_b32 s23, v57, s4
	v_readlane_b32 s41, v59, s4
	v_readlane_b32 s14, v71, s4
	v_readlane_b32 s15, v88, s4
	v_readlane_b32 s44, v45, s34
	v_readlane_b32 s4, v47, s34
	v_readlane_b32 s45, v51, s34
	v_readlane_b32 s5, v49, s34
	v_readlane_b32 s46, v53, s34
	v_readlane_b32 s68, v55, s34
	v_readlane_b32 s47, v57, s34
	v_readlane_b32 s69, v59, s34
	v_readlane_b32 s28, v71, s34
	v_readlane_b32 s29, v88, s34
	v_readlane_b32 s48, v45, s35
	v_readlane_b32 s58, v47, s35
	v_readlane_b32 s49, v51, s35
	v_readlane_b32 s59, v49, s35
	v_readlane_b32 s50, v53, s35
	v_readlane_b32 s60, v55, s35
	v_readlane_b32 s51, v57, s35
	v_readlane_b32 s61, v59, s35
	v_readlane_b32 s36, v71, s35
	v_readlane_b32 s37, v88, s35
	v_readlane_b32 s0, v47, s57
	v_readlane_b32 s1, v49, s57
	v_readlane_b32 s34, v55, s57
	v_readlane_b32 s35, v59, s57
	v_readlane_b32 s64, v47, s43
	v_readlane_b32 s65, v49, s43
	v_readlane_b32 s92, v55, s43
	v_readlane_b32 s93, v59, s43
	v_readlane_b32 s62, v45, s57
	v_readlane_b32 s63, v51, s57
	v_readlane_b32 s66, v53, s57
	v_readlane_b32 s67, v57, s57
	v_readlane_b32 s52, v45, s43
	v_readlane_b32 s53, v51, s43
	s_waitcnt vmcnt(16)
	v_accvgpr_read_b32 v24, a38
	v_accvgpr_read_b32 v70, a39
	v_accvgpr_read_b32 v22, a40
	v_accvgpr_read_b32 v20, a41
	v_accvgpr_read_b32 v76, a42
	v_accvgpr_read_b32 v60, a43
	v_accvgpr_read_b32 v66, a44
	v_accvgpr_read_b32 v64, a45
	v_accvgpr_read_b32 v62, a46
	v_accvgpr_read_b32 v26, a47
	v_accvgpr_read_b32 v18, a48
	v_accvgpr_read_b32 v14, a49
	v_accvgpr_read_b32 v12, a50
	v_accvgpr_read_b32 v8, a51
	v_accvgpr_read_b32 v10, a52
	v_accvgpr_read_b32 v16, a53
	v_pk_mul_f32 v[72:73], v[24:25], s[0:1] op_sel_hi:[0,1]
	v_pk_mul_f32 v[78:79], v[24:25], s[34:35] op_sel_hi:[0,1]
	v_readlane_b32 s54, v53, s43
	v_readlane_b32 s55, v57, s43
	v_readlane_b32 s56, v71, s57
	v_readlane_b32 s57, v88, s57
	v_readlane_b32 s0, v47, s33
	v_readlane_b32 s1, v49, s33
	v_pk_mul_f32 v[74:75], v[70:71], s[4:5] op_sel_hi:[0,1]
	v_readlane_b32 s4, v55, s33
	v_readlane_b32 s5, v59, s33
	v_pk_mul_f32 v[80:81], v[66:67], s[64:65] op_sel_hi:[0,1]
	v_pk_mul_f32 v[102:103], v[66:67], s[92:93] op_sel_hi:[0,1]
	v_pk_fma_f32 v[72:73], v[16:17], s[62:63], v[72:73] op_sel_hi:[0,1,1]
	v_pk_fma_f32 v[78:79], v[16:17], s[66:67], v[78:79] op_sel_hi:[0,1,1]
	v_mov_b32_e32 v17, v24
	v_pk_mul_f32 v[104:105], v[64:65], s[24:25] op_sel_hi:[0,1]
	v_pk_mul_f32 v[112:113], v[64:65], s[26:27] op_sel_hi:[0,1]
	v_pk_mul_f32 v[114:115], v[62:63], s[94:95] op_sel_hi:[0,1]
	v_pk_mul_f32 v[116:117], v[62:63], s[96:97] op_sel_hi:[0,1]
	v_pk_mul_f32 v[118:119], v[26:27], s[38:39] op_sel_hi:[0,1]
	v_readlane_b32 vcc_lo, v45, s33
	v_readlane_b32 vcc_hi, v51, s33
	v_readlane_b32 s34, v53, s33
	v_readlane_b32 s35, v57, s33
	v_pk_fma_f32 v[80:81], v[60:61], s[52:53], v[80:81] op_sel_hi:[0,1,1]
	v_pk_fma_f32 v[102:103], v[60:61], s[54:55], v[102:103] op_sel_hi:[0,1,1]
	v_mov_b32_e32 v61, v66
	v_pk_mul_f32 v[16:17], v[16:17], s[56:57]
	v_pk_fma_f32 v[66:67], v[18:19], s[10:11], v[104:105] op_sel_hi:[0,1,1]
	v_pk_fma_f32 v[104:105], v[18:19], s[12:13], v[112:113] op_sel_hi:[0,1,1]
	v_mov_b32_e32 v19, v64
	v_pk_fma_f32 v[64:65], v[14:15], s[16:17], v[114:115] op_sel_hi:[0,1,1]
	v_pk_fma_f32 v[112:113], v[14:15], s[18:19], v[116:117] op_sel_hi:[0,1,1]
	v_mov_b32_e32 v15, v62
	v_pk_fma_f32 v[62:63], v[12:13], s[20:21], v[118:119] op_sel_hi:[0,1,1]
	v_pk_mul_f32 v[116:117], v[10:11], s[0:1] op_sel_hi:[0,1]
	v_pk_mul_f32 v[118:119], v[10:11], s[4:5] op_sel_hi:[0,1]
	v_pk_mul_f32 v[68:69], v[70:71], s[68:69] op_sel_hi:[0,1]
	v_readlane_b32 s68, v71, s33
	v_readlane_b32 s69, v88, s33
	v_add_f32_e32 v11, v16, v17
	v_pk_mul_f32 v[16:17], v[18:19], s[6:7]
	v_pk_fma_f32 v[18:19], v[8:9], vcc, v[116:117] op_sel_hi:[0,1,1]
	v_pk_fma_f32 v[116:117], v[8:9], s[34:35], v[118:119] op_sel_hi:[0,1,1]
	v_mov_b32_e32 v9, v10
	v_pk_mul_f32 v[8:9], v[8:9], s[68:69]
	v_pk_mul_f32 v[120:121], v[26:27], s[40:41] op_sel_hi:[0,1]
	v_add_f32_e32 v8, v8, v9
	v_pk_fma_f32 v[114:115], v[12:13], s[22:23], v[120:121] op_sel_hi:[0,1,1]
	v_mov_b32_e32 v13, v26
	v_pk_mul_f32 v[14:15], v[14:15], s[8:9]
	v_add_f32_e32 v16, v16, v17
	v_pk_add_f32 v[2:3], v[2:3], v[18:19]
	v_pk_add_f32 v[0:1], v[0:1], v[116:117]
	v_add_f32_e32 v8, v43, v8
	v_pk_mul_f32 v[30:31], v[76:77], s[58:59] op_sel_hi:[0,1]
	v_pk_mul_f32 v[32:33], v[76:77], s[60:61] op_sel_hi:[0,1]
	v_pk_fma_f32 v[74:75], v[22:23], s[44:45], v[74:75] op_sel_hi:[0,1,1]
	v_pk_fma_f32 v[68:69], v[22:23], s[46:47], v[68:69] op_sel_hi:[0,1,1]
	v_mov_b32_e32 v23, v70
	v_pk_mul_f32 v[12:13], v[12:13], s[14:15]
	v_add_f32_e32 v14, v14, v15
	v_pk_add_f32 v[2:3], v[2:3], v[66:67]
	v_pk_add_f32 v[0:1], v[0:1], v[104:105]
	v_add_f32_e32 v8, v8, v16
	v_pk_fma_f32 v[30:31], v[20:21], s[48:49], v[30:31] op_sel_hi:[0,1,1]
	v_pk_fma_f32 v[32:33], v[20:21], s[50:51], v[32:33] op_sel_hi:[0,1,1]
	v_mov_b32_e32 v21, v76
	v_pk_mul_f32 v[22:23], v[22:23], s[28:29]
	v_add_f32_e32 v12, v12, v13
	v_pk_add_f32 v[2:3], v[2:3], v[64:65]
	v_pk_add_f32 v[0:1], v[0:1], v[112:113]
	v_add_f32_e32 v8, v8, v14
	v_readlane_b32 s42, v71, s43
	v_readlane_b32 s43, v88, s43
	v_pk_mul_f32 v[20:21], v[20:21], s[36:37]
	v_add_f32_e32 v10, v22, v23
	v_pk_add_f32 v[2:3], v[2:3], v[62:63]
	v_pk_add_f32 v[0:1], v[0:1], v[114:115]
	v_add_f32_e32 v8, v8, v12
	v_pk_mul_f32 v[60:61], v[60:61], s[42:43]
	v_add_f32_e32 v20, v20, v21
	v_pk_add_f32 v[2:3], v[2:3], v[74:75]
	v_pk_add_f32 v[0:1], v[0:1], v[68:69]
	v_add_f32_e32 v8, v8, v10
	v_add_f32_e32 v21, v60, v61
	v_pk_add_f32 v[2:3], v[2:3], v[30:31]
	v_pk_add_f32 v[0:1], v[0:1], v[32:33]
	v_add_f32_e32 v8, v8, v20
	s_add_i32 s33, s33, 8
	v_pk_add_f32 v[2:3], v[2:3], v[80:81]
	v_pk_add_f32 v[0:1], v[0:1], v[102:103]
	v_add_f32_e32 v8, v8, v21
	v_pk_add_f32 v[2:3], v[2:3], v[72:73]
	v_pk_add_f32 v[0:1], v[0:1], v[78:79]
	v_add_f32_e32 v43, v8, v11
	s_add_i32 s0, s33, 1
	s_add_i32 s1, s33, 2
	s_add_i32 s4, s33, 3
	s_add_i32 s34, s33, 4
	s_add_i32 s35, s33, 5
	s_add_i32 s57, s33, 7
	s_add_i32 s43, s33, 6
	v_readlane_b32 s10, v45, s0
	v_readlane_b32 s24, v47, s0
	v_readlane_b32 s11, v51, s0
	v_readlane_b32 s25, v49, s0
	v_readlane_b32 s12, v53, s0
	v_readlane_b32 s26, v55, s0
	v_readlane_b32 s13, v57, s0
	v_readlane_b32 s27, v59, s0
	v_readlane_b32 s6, v71, s0
	v_readlane_b32 s7, v88, s0
	v_readlane_b32 s16, v45, s1
	v_readlane_b32 s94, v47, s1
	v_readlane_b32 s17, v51, s1
	v_readlane_b32 s95, v49, s1
	v_readlane_b32 s18, v53, s1
	v_readlane_b32 s96, v55, s1
	v_readlane_b32 s19, v57, s1
	v_readlane_b32 s97, v59, s1
	v_readlane_b32 s8, v71, s1
	v_readlane_b32 s9, v88, s1
	v_readlane_b32 s20, v45, s4
	v_readlane_b32 s38, v47, s4
	v_readlane_b32 s21, v51, s4
	v_readlane_b32 s39, v49, s4
	v_readlane_b32 s22, v53, s4
	v_readlane_b32 s40, v55, s4
	v_readlane_b32 s23, v57, s4
	v_readlane_b32 s41, v59, s4
	v_readlane_b32 s14, v71, s4
	v_readlane_b32 s15, v88, s4
	v_readlane_b32 s44, v45, s34
	v_readlane_b32 s4, v47, s34
	v_readlane_b32 s45, v51, s34
	v_readlane_b32 s5, v49, s34
	v_readlane_b32 s46, v53, s34
	v_readlane_b32 s68, v55, s34
	v_readlane_b32 s47, v57, s34
	v_readlane_b32 s69, v59, s34
	v_readlane_b32 s28, v71, s34
	v_readlane_b32 s29, v88, s34
	v_readlane_b32 s48, v45, s35
	v_readlane_b32 s58, v47, s35
	v_readlane_b32 s49, v51, s35
	v_readlane_b32 s59, v49, s35
	v_readlane_b32 s50, v53, s35
	v_readlane_b32 s60, v55, s35
	v_readlane_b32 s51, v57, s35
	v_readlane_b32 s61, v59, s35
	v_readlane_b32 s36, v71, s35
	v_readlane_b32 s37, v88, s35
	v_readlane_b32 s0, v47, s57
	v_readlane_b32 s1, v49, s57
	v_readlane_b32 s34, v55, s57
	v_readlane_b32 s35, v59, s57
	v_readlane_b32 s64, v47, s43
	v_readlane_b32 s65, v49, s43
	v_readlane_b32 s92, v55, s43
	v_readlane_b32 s93, v59, s43
	v_readlane_b32 s62, v45, s57
	v_readlane_b32 s63, v51, s57
	v_readlane_b32 s66, v53, s57
	v_readlane_b32 s67, v57, s57
	v_readlane_b32 s52, v45, s43
	v_readlane_b32 s53, v51, s43
	s_waitcnt vmcnt(0)
	v_accvgpr_read_b32 v24, a54
	v_accvgpr_read_b32 v70, a55
	v_accvgpr_read_b32 v22, a56
	v_accvgpr_read_b32 v20, a57
	v_accvgpr_read_b32 v76, a58
	v_accvgpr_read_b32 v60, a59
	v_accvgpr_read_b32 v66, a60
	v_accvgpr_read_b32 v64, a61
	v_accvgpr_read_b32 v62, a62
	v_accvgpr_read_b32 v26, a63
	v_accvgpr_read_b32 v18, a64
	v_accvgpr_read_b32 v14, a65
	v_accvgpr_read_b32 v12, a66
	v_accvgpr_read_b32 v8, a67
	v_accvgpr_read_b32 v10, a68
	v_accvgpr_read_b32 v16, a69
	v_pk_mul_f32 v[72:73], v[24:25], s[0:1] op_sel_hi:[0,1]
	v_pk_mul_f32 v[78:79], v[24:25], s[34:35] op_sel_hi:[0,1]
	v_readlane_b32 s54, v53, s43
	v_readlane_b32 s55, v57, s43
	v_readlane_b32 s56, v71, s57
	v_readlane_b32 s57, v88, s57
	v_readlane_b32 s0, v47, s33
	v_readlane_b32 s1, v49, s33
	v_pk_mul_f32 v[74:75], v[70:71], s[4:5] op_sel_hi:[0,1]
	v_readlane_b32 s4, v55, s33
	v_readlane_b32 s5, v59, s33
	v_pk_mul_f32 v[80:81], v[66:67], s[64:65] op_sel_hi:[0,1]
	v_pk_mul_f32 v[102:103], v[66:67], s[92:93] op_sel_hi:[0,1]
	v_pk_fma_f32 v[72:73], v[16:17], s[62:63], v[72:73] op_sel_hi:[0,1,1]
	v_pk_fma_f32 v[78:79], v[16:17], s[66:67], v[78:79] op_sel_hi:[0,1,1]
	v_mov_b32_e32 v17, v24
	v_pk_mul_f32 v[104:105], v[64:65], s[24:25] op_sel_hi:[0,1]
	v_pk_mul_f32 v[112:113], v[64:65], s[26:27] op_sel_hi:[0,1]
	v_pk_mul_f32 v[114:115], v[62:63], s[94:95] op_sel_hi:[0,1]
	v_pk_mul_f32 v[116:117], v[62:63], s[96:97] op_sel_hi:[0,1]
	v_pk_mul_f32 v[118:119], v[26:27], s[38:39] op_sel_hi:[0,1]
	v_readlane_b32 vcc_lo, v45, s33
	v_readlane_b32 vcc_hi, v51, s33
	v_readlane_b32 s34, v53, s33
	v_readlane_b32 s35, v57, s33
	v_pk_fma_f32 v[80:81], v[60:61], s[52:53], v[80:81] op_sel_hi:[0,1,1]
	v_pk_fma_f32 v[102:103], v[60:61], s[54:55], v[102:103] op_sel_hi:[0,1,1]
	v_mov_b32_e32 v61, v66
	v_pk_mul_f32 v[16:17], v[16:17], s[56:57]
	v_pk_fma_f32 v[66:67], v[18:19], s[10:11], v[104:105] op_sel_hi:[0,1,1]
	v_pk_fma_f32 v[104:105], v[18:19], s[12:13], v[112:113] op_sel_hi:[0,1,1]
	v_mov_b32_e32 v19, v64
	v_pk_fma_f32 v[64:65], v[14:15], s[16:17], v[114:115] op_sel_hi:[0,1,1]
	v_pk_fma_f32 v[112:113], v[14:15], s[18:19], v[116:117] op_sel_hi:[0,1,1]
	v_mov_b32_e32 v15, v62
	v_pk_fma_f32 v[62:63], v[12:13], s[20:21], v[118:119] op_sel_hi:[0,1,1]
	v_pk_mul_f32 v[116:117], v[10:11], s[0:1] op_sel_hi:[0,1]
	v_pk_mul_f32 v[118:119], v[10:11], s[4:5] op_sel_hi:[0,1]
	v_pk_mul_f32 v[68:69], v[70:71], s[68:69] op_sel_hi:[0,1]
	v_readlane_b32 s68, v71, s33
	v_readlane_b32 s69, v88, s33
	v_add_f32_e32 v11, v16, v17
	v_pk_mul_f32 v[16:17], v[18:19], s[6:7]
	v_pk_fma_f32 v[18:19], v[8:9], vcc, v[116:117] op_sel_hi:[0,1,1]
	v_pk_fma_f32 v[116:117], v[8:9], s[34:35], v[118:119] op_sel_hi:[0,1,1]
	v_mov_b32_e32 v9, v10
	v_pk_mul_f32 v[8:9], v[8:9], s[68:69]
	v_pk_mul_f32 v[120:121], v[26:27], s[40:41] op_sel_hi:[0,1]
	v_add_f32_e32 v8, v8, v9
	v_pk_fma_f32 v[114:115], v[12:13], s[22:23], v[120:121] op_sel_hi:[0,1,1]
	v_mov_b32_e32 v13, v26
	v_pk_mul_f32 v[14:15], v[14:15], s[8:9]
	v_add_f32_e32 v16, v16, v17
	v_pk_add_f32 v[2:3], v[2:3], v[18:19]
	v_pk_add_f32 v[0:1], v[0:1], v[116:117]
	v_add_f32_e32 v8, v43, v8
	v_pk_mul_f32 v[30:31], v[76:77], s[58:59] op_sel_hi:[0,1]
	v_pk_mul_f32 v[32:33], v[76:77], s[60:61] op_sel_hi:[0,1]
	v_pk_fma_f32 v[74:75], v[22:23], s[44:45], v[74:75] op_sel_hi:[0,1,1]
	v_pk_fma_f32 v[68:69], v[22:23], s[46:47], v[68:69] op_sel_hi:[0,1,1]
	v_mov_b32_e32 v23, v70
	v_pk_mul_f32 v[12:13], v[12:13], s[14:15]
	v_add_f32_e32 v14, v14, v15
	v_pk_add_f32 v[2:3], v[2:3], v[66:67]
	v_pk_add_f32 v[0:1], v[0:1], v[104:105]
	v_add_f32_e32 v8, v8, v16
	v_pk_fma_f32 v[30:31], v[20:21], s[48:49], v[30:31] op_sel_hi:[0,1,1]
	v_pk_fma_f32 v[32:33], v[20:21], s[50:51], v[32:33] op_sel_hi:[0,1,1]
	v_mov_b32_e32 v21, v76
	v_pk_mul_f32 v[22:23], v[22:23], s[28:29]
	v_add_f32_e32 v12, v12, v13
	v_pk_add_f32 v[2:3], v[2:3], v[64:65]
	v_pk_add_f32 v[0:1], v[0:1], v[112:113]
	v_add_f32_e32 v8, v8, v14
	v_readlane_b32 s42, v71, s43
	v_readlane_b32 s43, v88, s43
	v_pk_mul_f32 v[20:21], v[20:21], s[36:37]
	v_add_f32_e32 v10, v22, v23
	v_pk_add_f32 v[2:3], v[2:3], v[62:63]
	v_pk_add_f32 v[0:1], v[0:1], v[114:115]
	v_add_f32_e32 v8, v8, v12
	v_pk_mul_f32 v[60:61], v[60:61], s[42:43]
	v_add_f32_e32 v20, v20, v21
	v_pk_add_f32 v[2:3], v[2:3], v[74:75]
	v_pk_add_f32 v[0:1], v[0:1], v[68:69]
	v_add_f32_e32 v8, v8, v10
	v_add_f32_e32 v21, v60, v61
	v_pk_add_f32 v[2:3], v[2:3], v[30:31]
	v_pk_add_f32 v[0:1], v[0:1], v[32:33]
	v_add_f32_e32 v8, v8, v20
	s_add_i32 s33, s33, 8
	v_pk_add_f32 v[2:3], v[2:3], v[80:81]
	v_pk_add_f32 v[0:1], v[0:1], v[102:103]
	v_add_f32_e32 v8, v8, v21
	s_cmp_eq_u32 s33, 64
	v_pk_add_f32 v[2:3], v[2:3], v[72:73]
	v_pk_add_f32 v[0:1], v[0:1], v[78:79]
	v_add_f32_e32 v43, v8, v11
	s_cbranch_scc0 .LBB0_55
	v_lshl_add_u32 v6, v41, 1, v25
	v_mul_hi_i32_i24_e32 v7, 0x1e000, v6
	v_mul_i32_i24_e32 v6, 0x1e000, v6
	v_lshl_add_u64 v[6:7], s[78:79], 0, v[6:7]
	v_lshl_add_u64 v[4:5], v[4:5], 2, v[6:7]
	v_add_co_u32_e32 v6, vcc, 0x6000, v4
	global_store_dword v[4:5], v2, off
	s_nop 0
	v_addc_co_u32_e32 v7, vcc, 0, v5, vcc
	v_add_co_u32_e32 v2, vcc, 0xc000, v4
	global_store_dword v[6:7], v3, off
	s_nop 0
	v_addc_co_u32_e32 v3, vcc, 0, v5, vcc
	global_store_dword v[2:3], v0, off
	v_add_co_u32_e32 v2, vcc, 0x12000, v4
	v_readlane_b32 s48, v126, 63
	s_nop 0
	v_addc_co_u32_e32 v3, vcc, 0, v5, vcc
	v_add_co_u32_e32 v0, vcc, 0x18000, v4
	s_mov_b32 s40, 0x24115d9a
	global_store_dword v[2:3], v1, off
	v_addc_co_u32_e32 v1, vcc, 0, v5, vcc
	v_readlane_b32 s49, v127, 0
	v_readlane_b32 s50, v127, 1
	v_readlane_b32 s51, v127, 2
	v_readlane_b32 s52, v127, 3
	v_readlane_b32 s53, v127, 4
	v_readlane_b32 s54, v127, 5
	v_readlane_b32 s55, v127, 6
	v_readlane_b32 s56, v127, 7
	v_readlane_b32 s57, v127, 8
	v_readlane_b32 s58, v127, 9
	v_readlane_b32 s59, v127, 10
	v_readlane_b32 s60, v127, 11
	v_readlane_b32 s61, v127, 12
	v_readlane_b32 s62, v127, 13
	v_readlane_b32 s63, v127, 14
	s_mov_b32 s41, 0x3fe7ff22
	global_store_dword v[0:1], v43, off
	s_branch .LBB0_8
